# V staged row-major in LDS and read with ds_read_b64_tr_b16 (no 2-byte scatter transpose); packed f32 VALU in the attention loops split into scalar ops
# speedup vs baseline: 1.0047x; 1.0047x over previous
.Llat_chunks:
	v_readlane_b32 s6, v255, 9
	v_ashrrev_i32_e32 v129, 3, v26
	v_lshl_add_u32 v14, v129, 1, v27
	v_cmp_gt_i32_e32 vcc, s6, v25
	s_and_saveexec_b64 s[4:5], vcc
	s_cbranch_execz .Llat_c0
	v_mad_u32_u24 v31, v148, s2, v146
	ds_write_b128 v31, v[202:205]
	v_mul_u32_u24_e32 v31, 0xc0, v148
	v_add_u32_e32 v31, v31, v146
	ds_write_b128 v31, v[206:209] offset:46080
.Llat_c0:
	s_or_b64 exec, exec, s[4:5]
	v_cmp_gt_i32_e32 vcc, s6, v30
	s_and_saveexec_b64 s[4:5], vcc
	s_cbranch_execz .Llat_c1
	v_mad_u32_u24 v31, v150, s2, v146
	ds_write_b128 v31, v[210:213]
	v_mul_u32_u24_e32 v31, 0xc0, v150
	v_add_u32_e32 v31, v31, v146
	ds_write_b128 v31, v[214:217] offset:46080
.Llat_c1:
	s_or_b64 exec, exec, s[4:5]
	v_cmp_gt_i32_e32 vcc, s6, v29
	s_and_saveexec_b64 s[4:5], vcc
	s_cbranch_execz .Llat_c2
	v_mad_u32_u24 v31, v152, s2, v146
	ds_write_b128 v31, v[218:221]
	v_mul_u32_u24_e32 v31, 0xc0, v152
	v_add_u32_e32 v31, v31, v146
	ds_write_b128 v31, v[222:225] offset:46080
.Llat_c2:
	s_or_b64 exec, exec, s[4:5]
	v_cmp_gt_i32_e32 vcc, s6, v28
	s_and_saveexec_b64 s[4:5], vcc
	s_cbranch_execz .Llat_c3
	v_mad_u32_u24 v31, v154, s2, v146
	ds_write_b128 v31, v[226:229]
	v_mul_u32_u24_e32 v31, 0xc0, v154
	v_add_u32_e32 v31, v31, v146
	ds_write_b128 v31, v[230:233] offset:46080
.Llat_c3:
	s_or_b64 exec, exec, s[4:5]
	v_cmp_gt_i32_e32 vcc, s6, v26
	s_and_saveexec_b64 s[4:5], vcc
	s_cbranch_execz .Llat_c4
	v_mad_u32_u24 v31, v129, s2, v146
	ds_write_b128 v31, v[234:237]
	v_mul_u32_u24_e32 v31, 0xc0, v129
	v_add_u32_e32 v31, v31, v146
	ds_write_b128 v31, v[242:245] offset:46080
.Llat_c4:
	s_or_b64 exec, exec, s[4:5]
	v_readlane_b32 s0, v255, 7
	v_readlane_b32 s1, v255, 8
	s_waitcnt vmcnt(0)
	v_mov_b32_e32 v15, 0
	s_andn2_b64 vcc, exec, s[0:1]
	v_cndmask_b32_e64 v14, 0, 1, s[0:1]
	s_nop 0
	v_cmp_ne_u32_e64 s[4:5], 1, v14
	s_cbranch_vccnz .LBB0_375
	v_cvt_pk_bf16_f32 v114, v6, v7
	v_cvt_pk_bf16_f32 v112, v10, v11
	v_cvt_pk_bf16_f32 v113, v12, v13
	v_cvt_pk_bf16_f32 v149, v8, v9
	v_cvt_pk_bf16_f32 v160, v20, v21
	v_cvt_pk_bf16_f32 v161, v22, v23
	v_cvt_pk_bf16_f32 v162, v16, v17
	v_cvt_pk_bf16_f32 v163, v18, v19
	v_cvt_pk_bf16_f32 v118, v32, v33
	v_cvt_pk_bf16_f32 v116, v36, v37
	v_cvt_pk_bf16_f32 v117, v38, v39
	v_cvt_pk_bf16_f32 v153, v34, v35
	v_cvt_pk_bf16_f32 v164, v44, v45
	v_cvt_pk_bf16_f32 v165, v46, v47
	v_cvt_pk_bf16_f32 v166, v40, v41
	v_cvt_pk_bf16_f32 v167, v42, v43
	v_cvt_pk_bf16_f32 v122, v48, v49
	v_cvt_pk_bf16_f32 v120, v52, v53
	v_cvt_pk_bf16_f32 v121, v54, v55
	v_cvt_pk_bf16_f32 v176, v50, v51
	v_cvt_pk_bf16_f32 v168, v60, v61
	v_cvt_pk_bf16_f32 v169, v62, v63
	v_cvt_pk_bf16_f32 v170, v56, v57
	v_cvt_pk_bf16_f32 v171, v58, v59
	v_cvt_pk_bf16_f32 v126, v180, v181
	v_cvt_pk_bf16_f32 v124, v184, v185
	v_cvt_pk_bf16_f32 v125, v186, v187
	v_cvt_pk_bf16_f32 v177, v182, v183
	v_cvt_pk_bf16_f32 v172, v192, v193
	v_cvt_pk_bf16_f32 v173, v194, v195
	v_cvt_pk_bf16_f32 v174, v188, v189
	v_cvt_pk_bf16_f32 v175, v190, v191
	s_branch .LBB0_376
.LBB0_375:
	v_mov_b32_e32 v112, 0
	v_mov_b32_e32 v113, 0
	v_mov_b32_e32 v114, 0
	v_mov_b32_e32 v149, 0
	v_mov_b32_e32 v160, 0
	v_mov_b32_e32 v161, 0
	v_mov_b32_e32 v162, 0
	v_mov_b32_e32 v163, 0
	v_mov_b32_e32 v116, 0
	v_mov_b32_e32 v117, 0
	v_mov_b32_e32 v118, 0
	v_mov_b32_e32 v153, 0
	v_mov_b32_e32 v164, 0
	v_mov_b32_e32 v165, 0
	v_mov_b32_e32 v166, 0
	v_mov_b32_e32 v167, 0
	v_mov_b32_e32 v120, 0
	v_mov_b32_e32 v121, 0
	v_mov_b32_e32 v122, 0
	v_mov_b32_e32 v176, 0
	v_mov_b32_e32 v168, 0
	v_mov_b32_e32 v169, 0
	v_mov_b32_e32 v170, 0
	v_mov_b32_e32 v171, 0
	v_mov_b32_e32 v124, 0
	v_mov_b32_e32 v125, 0
	v_mov_b32_e32 v126, 0
	v_mov_b32_e32 v177, 0
	v_mov_b32_e32 v172, 0
	v_mov_b32_e32 v173, 0
	v_mov_b32_e32 v174, 0
	v_mov_b32_e32 v175, 0
.LBB0_376:
	v_bfe_u32 v31, v24, 2, 2
	v_mul_u32_u24_e32 v235, 0xc0, v31
	v_lshrrev_b32_e32 v31, 5, v24
	v_lshl_add_u32 v235, v31, 8, v235
	v_lshl_add_u32 v235, v31, 9, v235
	v_bfe_u32 v31, v24, 4, 1
	v_lshl_add_u32 v235, v31, 5, v235
	v_and_b32_e32 v31, 3, v24
	v_lshl_add_u32 v235, v31, 3, v235
	v_readlane_b32 s6, v255, 21
	v_readlane_b32 s7, v255, 22
	v_cmp_eq_u32_e64 s[0:1], 0, v5
	s_andn2_b64 vcc, exec, s[6:7]
	s_movk_i32 s2, 0x288
	s_movk_i32 s6, 0x90
	v_lshlrev_b32_e32 v119, 2, v5
	s_waitcnt vmcnt(0)
	v_mul_f32_e32 v183, 0x3fb8aa3b, v1
	v_cndmask_b32_e64 v182, 0, 1.0, s[0:1]
	v_mad_u32_u24 v123, v2, s2, v198
	v_mad_u32_u24 v127, v2, s6, v0
	s_waitcnt lgkmcnt(0)
	s_barrier
	s_cbranch_vccnz .LBB0_386
	v_mbcnt_hi_u32_b32 v1, -1, v197
	v_readfirstlane_b32 s32, v4
	v_and_b32_e32 v5, 64, v1
	v_mad_u32_u24 v129, v2, s6, v0
	v_readlane_b32 s6, v255, 25
	v_add_u32_e32 v151, 0x41, v4
	v_xor_b32_e32 v4, 32, v1
	v_add_u32_e32 v5, 64, v5
	v_add3_u32 v0, s6, v3, v2
	v_readlane_b32 s6, v255, 28
	v_cmp_lt_i32_e32 vcc, v4, v5
	v_sub_u32_e32 v179, v0, v119
	v_add_u32_e32 v0, s6, v119
	v_cndmask_b32_e32 v1, v1, v4, vcc
	v_sub_u32_e32 v0, v0, v2
	v_mov_b32_e32 v16, 0
	v_lshlrev_b32_e32 v155, 2, v1
	s_movk_i32 s2, 0x90
	v_sub_u32_e32 v180, v0, v3
	v_readlane_b32 s19, v255, 26
	v_mov_b32_e32 v181, v123
	v_readlane_b32 s21, v255, 20
	v_mov_b32_e32 v17, v16
	v_mov_b32_e32 v18, v16
	v_mov_b32_e32 v19, v16
	v_mov_b32_e32 v20, v16
	v_mov_b32_e32 v21, v16
	v_mov_b32_e32 v22, v16
	v_mov_b32_e32 v23, v16
	v_mov_b32_e32 v24, v16
	v_mov_b32_e32 v25, v16
	v_mov_b32_e32 v26, v16
	v_mov_b32_e32 v27, v16
	v_mov_b32_e32 v28, v16
	v_mov_b32_e32 v29, v16
	v_mov_b32_e32 v30, v16
	v_mov_b32_e32 v31, v16
	v_mov_b32_e32 v0, v16
	v_mov_b32_e32 v1, v16
	v_mov_b32_e32 v2, v16
	v_mov_b32_e32 v3, v16
	v_mov_b32_e32 v4, v16
	v_mov_b32_e32 v5, v16
	v_mov_b32_e32 v6, v16
	v_mov_b32_e32 v7, v16
	v_mov_b32_e32 v8, v16
	v_mov_b32_e32 v9, v16
	v_mov_b32_e32 v10, v16
	v_mov_b32_e32 v11, v16
	v_mov_b32_e32 v12, v16
	v_mov_b32_e32 v13, v16
	v_mov_b32_e32 v14, v16
	v_mov_b32_e32 v15, v16
	v_mov_b32_e32 v234, v235
	ds_read_b128 v[202:205], v129
	ds_read_b128 v[206:209], v129 offset:32
	ds_read_b128 v[210:213], v129 offset:64
	ds_read_b128 v[214:217], v129 offset:96
	ds_read_b128 v[218:221], v129 offset:4608
	ds_read_b128 v[222:225], v129 offset:4640
	ds_read_b128 v[226:229], v129 offset:4672
	ds_read_b128 v[230:233], v129 offset:4704
	v_add_u32_e32 v129, 0x2400, v129
.Llat1_top:
	s_waitcnt lgkmcnt(7)
	v_mfma_f32_32x32x16_bf16 v[48:63], v[202:205], v[96:99], 0
	ds_read_b64_tr_b16 v[202:203], v234 offset:46080
	ds_read_b64_tr_b16 v[204:205], v234 offset:47616
	s_waitcnt lgkmcnt(8)
	v_mfma_f32_32x32x16_bf16 v[48:63], v[206:209], v[100:103], v[48:63]
	ds_read_b64_tr_b16 v[206:207], v234 offset:49152
	ds_read_b64_tr_b16 v[208:209], v234 offset:50688
	s_waitcnt lgkmcnt(9)
	v_mfma_f32_32x32x16_bf16 v[48:63], v[210:213], v[104:107], v[48:63]
	ds_read_b64_tr_b16 v[210:211], v234 offset:46144
	ds_read_b64_tr_b16 v[212:213], v234 offset:47680
	s_waitcnt lgkmcnt(10)
	v_mfma_f32_32x32x16_bf16 v[48:63], v[214:217], v[108:111], v[48:63]
	ds_read_b64_tr_b16 v[214:215], v234 offset:49216
	ds_read_b64_tr_b16 v[216:217], v234 offset:50752
	s_waitcnt lgkmcnt(11)
	v_mfma_f32_32x32x16_bf16 v[32:47], v[218:221], v[96:99], 0
	ds_read_b64_tr_b16 v[218:219], v234 offset:52224
	ds_read_b64_tr_b16 v[220:221], v234 offset:53760
	s_waitcnt lgkmcnt(12)
	v_mfma_f32_32x32x16_bf16 v[32:47], v[222:225], v[100:103], v[32:47]
	ds_read_b64_tr_b16 v[222:223], v234 offset:55296
	ds_read_b64_tr_b16 v[224:225], v234 offset:56832
	s_waitcnt lgkmcnt(13)
	v_mfma_f32_32x32x16_bf16 v[32:47], v[226:229], v[104:107], v[32:47]
	ds_read_b64_tr_b16 v[226:227], v234 offset:52288
	ds_read_b64_tr_b16 v[228:229], v234 offset:53824
	s_waitcnt lgkmcnt(13)
	v_mfma_f32_32x32x16_bf16 v[32:47], v[230:233], v[108:111], v[32:47]
	ds_read_b64_tr_b16 v[230:231], v234 offset:55360
	ds_read_b64_tr_b16 v[232:233], v234 offset:56896
	s_cmp_lg_u64 s[4:5], 0
	s_cbranch_scc1 .Llat1_plainmax
	s_sub_i32 s63, s19, s32
	s_add_i32 s63, s63, 0x61
	s_cmp_lt_u32 s63, 0xa3
	s_cbranch_scc1 .Llat1_plainmax
	v_add_u32_e32 v236, 59, v179
	v_cmp_lt_u32_e32 vcc, s17, v236
	v_add_u32_e32 v237, 57, v179
	s_nop 0
	v_cndmask_b32_e32 v48, v252, v48, vcc
	v_cmp_gt_u32_e32 vcc, s31, v180
	s_nop 1
	v_cndmask_b32_e32 v49, v252, v49, vcc
	v_cmp_lt_u32_e32 vcc, s17, v237
	v_add_u32_e32 v237, 56, v179
	v_max3_f32 v236, v48, s16, v49
	v_cndmask_b32_e32 v50, v252, v50, vcc
	v_cmp_lt_u32_e32 vcc, s17, v237
	v_add_u32_e32 v237, 51, v179
	s_nop 0
	v_cndmask_b32_e32 v51, v252, v51, vcc
	v_cmp_lt_u32_e32 vcc, s17, v237
	v_add_u32_e32 v237, 50, v179
	v_max3_f32 v236, v236, v50, v51
	v_cndmask_b32_e32 v52, v252, v52, vcc
	v_cmp_lt_u32_e32 vcc, s17, v237
	v_add_u32_e32 v237, 49, v179
	s_nop 0
	v_cndmask_b32_e32 v53, v252, v53, vcc
	v_cmp_lt_u32_e32 vcc, s17, v237
	v_add_u32_e32 v237, 48, v179
	v_max3_f32 v236, v236, v52, v53
	v_cndmask_b32_e32 v54, v252, v54, vcc
	v_cmp_lt_u32_e32 vcc, s17, v237
	v_add_u32_e32 v237, 43, v179
	s_nop 0
	v_cndmask_b32_e32 v55, v252, v55, vcc
	v_cmp_lt_u32_e32 vcc, s17, v237
	v_add_u32_e32 v237, 42, v179
	v_max3_f32 v236, v236, v54, v55
	v_cndmask_b32_e32 v56, v252, v56, vcc
	v_cmp_lt_u32_e32 vcc, s17, v237
	v_add_u32_e32 v237, 41, v179
	s_nop 0
	v_cndmask_b32_e32 v57, v252, v57, vcc
	v_cmp_lt_u32_e32 vcc, s17, v237
	v_add_u32_e32 v237, 40, v179
	v_max3_f32 v236, v236, v56, v57
	v_cndmask_b32_e32 v58, v252, v58, vcc
	v_cmp_lt_u32_e32 vcc, s17, v237
	v_add_u32_e32 v237, 35, v179
	s_nop 0
	v_cndmask_b32_e32 v59, v252, v59, vcc
	v_cmp_lt_u32_e32 vcc, s17, v237
	v_add_u32_e32 v237, 34, v179
	v_max3_f32 v236, v236, v58, v59
	v_cndmask_b32_e32 v60, v252, v60, vcc
	v_cmp_lt_u32_e32 vcc, s17, v237
	v_add_u32_e32 v237, 33, v179
	s_nop 0
	v_cndmask_b32_e32 v61, v252, v61, vcc
	v_cmp_lt_u32_e32 vcc, s17, v237
	v_add_u32_e32 v237, 32, v179
	v_max3_f32 v236, v236, v60, v61
	v_cndmask_b32_e32 v62, v252, v62, vcc
	v_cmp_lt_u32_e32 vcc, s17, v237
	v_add_u32_e32 v237, 27, v179
	s_nop 0
	v_cndmask_b32_e32 v63, v252, v63, vcc
	v_cmp_lt_u32_e32 vcc, s17, v237
	v_add_u32_e32 v237, 26, v179
	v_max3_f32 v236, v236, v62, v63
	v_cndmask_b32_e32 v32, v252, v32, vcc
	v_cmp_lt_u32_e32 vcc, s17, v237
	v_add_u32_e32 v237, 25, v179
	s_nop 0
	v_cndmask_b32_e32 v33, v252, v33, vcc
	v_cmp_lt_u32_e32 vcc, s17, v237
	v_add_u32_e32 v237, 24, v179
	v_max3_f32 v236, v236, v32, v33
	v_cndmask_b32_e32 v34, v252, v34, vcc
	v_cmp_lt_u32_e32 vcc, s17, v237
	v_add_u32_e32 v237, 19, v179
	s_nop 0
	v_cndmask_b32_e32 v35, v252, v35, vcc
	v_cmp_lt_u32_e32 vcc, s17, v237
	v_add_u32_e32 v237, 18, v179
	v_max3_f32 v236, v236, v34, v35
	v_cndmask_b32_e32 v36, v252, v36, vcc
	v_cmp_lt_u32_e32 vcc, s17, v237
	v_add_u32_e32 v237, 17, v179
	s_nop 0
	v_cndmask_b32_e32 v37, v252, v37, vcc
	v_cmp_lt_u32_e32 vcc, s17, v237
	v_add_u32_e32 v237, 16, v179
	v_max3_f32 v236, v236, v36, v37
	v_cndmask_b32_e32 v38, v252, v38, vcc
	v_cmp_lt_u32_e32 vcc, s17, v237
	v_add_u32_e32 v237, 11, v179
	s_nop 0
	v_cndmask_b32_e32 v39, v252, v39, vcc
	v_cmp_lt_u32_e32 vcc, s17, v237
	v_add_u32_e32 v237, 10, v179
	v_max3_f32 v236, v236, v38, v39
	v_cndmask_b32_e32 v40, v252, v40, vcc
	v_cmp_lt_u32_e32 vcc, s17, v237
	v_add_u32_e32 v237, 9, v179
	s_nop 0
	v_cndmask_b32_e32 v41, v252, v41, vcc
	v_cmp_lt_u32_e32 vcc, s17, v237
	v_add_u32_e32 v237, 8, v179
	v_max3_f32 v236, v236, v40, v41
	v_cndmask_b32_e32 v42, v252, v42, vcc
	v_cmp_lt_u32_e32 vcc, s17, v237
	v_add_u32_e32 v237, 3, v179
	s_nop 0
	v_cndmask_b32_e32 v43, v252, v43, vcc
	v_cmp_lt_u32_e32 vcc, s17, v237
	v_add_u32_e32 v237, 2, v179
	v_max3_f32 v236, v236, v42, v43
	v_cndmask_b32_e32 v44, v252, v44, vcc
	v_cmp_lt_u32_e32 vcc, s17, v237
	v_add_u32_e32 v237, 1, v179
	s_nop 0
	v_cndmask_b32_e32 v45, v252, v45, vcc
	v_cmp_lt_u32_e32 vcc, s17, v237
	v_max3_f32 v236, v236, v44, v45
	s_nop 0
	v_cndmask_b32_e32 v46, v252, v46, vcc
	v_cmp_lt_u32_e32 vcc, s17, v179
	s_nop 1
	v_cndmask_b32_e32 v47, v252, v47, vcc
	v_max3_f32 v236, v236, v46, v47
	s_branch .Llat1_maxdone

.Llat1_maxdone:
	ds_bpermute_b32 v237, v155, v236
	s_waitcnt lgkmcnt(0)
	v_max3_f32 v236, v183, v236, v237
	v_sub_f32_e32 v238, v183, v236
	v_sub_f32_e32 v48, v48, v236
	v_sub_f32_e32 v49, v49, v236
	v_sub_f32_e32 v50, v50, v236
	v_sub_f32_e32 v51, v51, v236
	v_sub_f32_e32 v52, v52, v236
	v_sub_f32_e32 v53, v53, v236
	v_sub_f32_e32 v54, v54, v236
	v_sub_f32_e32 v55, v55, v236
	v_sub_f32_e32 v56, v56, v236
	v_sub_f32_e32 v57, v57, v236
	v_sub_f32_e32 v58, v58, v236
	v_sub_f32_e32 v59, v59, v236
	v_sub_f32_e32 v60, v60, v236
	v_sub_f32_e32 v61, v61, v236
	v_sub_f32_e32 v62, v62, v236
	v_sub_f32_e32 v63, v63, v236
	v_exp_f32_e32 v238, v238
	v_exp_f32_e32 v48, v48
	v_exp_f32_e32 v49, v49
	v_exp_f32_e32 v50, v50
	v_exp_f32_e32 v51, v51
	v_exp_f32_e32 v52, v52
	v_exp_f32_e32 v53, v53
	v_exp_f32_e32 v54, v54
	v_exp_f32_e32 v55, v55
	v_exp_f32_e32 v56, v56
	v_exp_f32_e32 v57, v57
	v_exp_f32_e32 v58, v58
	v_exp_f32_e32 v59, v59
	v_exp_f32_e32 v60, v60
	v_exp_f32_e32 v61, v61
	v_exp_f32_e32 v62, v62
	v_exp_f32_e32 v63, v63
	v_add_f32_e32 v242, 0, v48
	v_add_f32_e32 v243, 0, v49
	v_add_f32_e32 v242, v50, v242
	v_add_f32_e32 v243, v51, v243
	v_add_f32_e32 v242, v52, v242
	v_add_f32_e32 v243, v53, v243
	v_add_f32_e32 v242, v54, v242
	v_add_f32_e32 v243, v55, v243
	v_add_f32_e32 v242, v56, v242
	v_add_f32_e32 v243, v57, v243
	v_add_f32_e32 v242, v58, v242
	v_add_f32_e32 v243, v59, v243
	v_add_f32_e32 v242, v60, v242
	v_add_f32_e32 v243, v61, v243
	v_add_f32_e32 v242, v62, v242
	v_add_f32_e32 v243, v63, v243
	v_cvt_pk_bf16_f32 v48, v48, v49
	v_cvt_pk_bf16_f32 v49, v50, v51
	v_cvt_pk_bf16_f32 v50, v52, v53
	v_cvt_pk_bf16_f32 v51, v54, v55
	v_cvt_pk_bf16_f32 v52, v56, v57
	v_cvt_pk_bf16_f32 v53, v58, v59
	v_cvt_pk_bf16_f32 v54, v60, v61
	v_cvt_pk_bf16_f32 v55, v62, v63
	v_mul_f32_e32 v16, v16, v238
	v_mul_f32_e32 v17, v17, v238
	v_mul_f32_e32 v18, v18, v238
	v_mul_f32_e32 v19, v19, v238
	v_mul_f32_e32 v20, v20, v238
	v_mul_f32_e32 v21, v21, v238
	v_mul_f32_e32 v22, v22, v238
	v_mul_f32_e32 v23, v23, v238
	v_mul_f32_e32 v24, v24, v238
	v_mul_f32_e32 v25, v25, v238
	v_mul_f32_e32 v26, v26, v238
	v_mul_f32_e32 v27, v27, v238
	v_mul_f32_e32 v28, v28, v238
	v_mul_f32_e32 v29, v29, v238
	v_mul_f32_e32 v30, v30, v238
	v_mul_f32_e32 v31, v31, v238
	v_mul_f32_e32 v0, v0, v238
	v_mul_f32_e32 v1, v1, v238
	v_mul_f32_e32 v2, v2, v238
	v_mul_f32_e32 v3, v3, v238
	v_mul_f32_e32 v4, v4, v238
	v_mul_f32_e32 v5, v5, v238
	v_mul_f32_e32 v6, v6, v238
	v_mul_f32_e32 v7, v7, v238
	v_mul_f32_e32 v8, v8, v238
	v_mul_f32_e32 v9, v9, v238
	v_mul_f32_e32 v10, v10, v238
	v_mul_f32_e32 v11, v11, v238
	v_mul_f32_e32 v12, v12, v238
	v_mul_f32_e32 v13, v13, v238
	v_mul_f32_e32 v14, v14, v238
	v_mul_f32_e32 v15, v15, v238
	v_mfma_f32_32x32x16_bf16 v[16:31], v[202:205], v[48:51], v[16:31]
	ds_read_b128 v[202:205], v129
	v_sub_f32_e32 v32, v32, v236
	v_sub_f32_e32 v33, v33, v236
	v_sub_f32_e32 v34, v34, v236
	v_sub_f32_e32 v35, v35, v236
	v_sub_f32_e32 v36, v36, v236
	v_sub_f32_e32 v37, v37, v236
	v_sub_f32_e32 v38, v38, v236
	v_sub_f32_e32 v39, v39, v236
	v_sub_f32_e32 v40, v40, v236
	v_sub_f32_e32 v41, v41, v236
	v_sub_f32_e32 v42, v42, v236
	v_sub_f32_e32 v43, v43, v236
	v_sub_f32_e32 v44, v44, v236
	v_sub_f32_e32 v45, v45, v236
	v_sub_f32_e32 v46, v46, v236
	v_sub_f32_e32 v47, v47, v236
	v_exp_f32_e32 v32, v32
	v_exp_f32_e32 v33, v33
	v_mfma_f32_32x32x16_bf16 v[16:31], v[206:209], v[52:55], v[16:31]
	ds_read_b128 v[206:209], v129 offset:32
	v_exp_f32_e32 v34, v34
	v_exp_f32_e32 v35, v35
	v_exp_f32_e32 v36, v36
	v_exp_f32_e32 v37, v37
	v_exp_f32_e32 v38, v38
	v_exp_f32_e32 v39, v39
	v_exp_f32_e32 v40, v40
	v_exp_f32_e32 v41, v41
	v_exp_f32_e32 v42, v42
	v_exp_f32_e32 v43, v43
	v_mfma_f32_32x32x16_bf16 v[0:15], v[210:213], v[48:51], v[0:15]
	ds_read_b128 v[210:213], v129 offset:64
	v_exp_f32_e32 v44, v44
	v_exp_f32_e32 v45, v45
	v_exp_f32_e32 v46, v46
	v_exp_f32_e32 v47, v47
	v_add_f32_e32 v242, v32, v242
	v_add_f32_e32 v243, v33, v243
	v_add_f32_e32 v242, v34, v242
	v_add_f32_e32 v243, v35, v243
	v_add_f32_e32 v242, v36, v242
	v_add_f32_e32 v243, v37, v243
	v_add_f32_e32 v242, v38, v242
	v_add_f32_e32 v243, v39, v243
	v_add_f32_e32 v242, v40, v242
	v_add_f32_e32 v243, v41, v243
	v_add_f32_e32 v242, v42, v242
	v_add_f32_e32 v243, v43, v243
	v_mfma_f32_32x32x16_bf16 v[0:15], v[214:217], v[52:55], v[0:15]
	ds_read_b128 v[214:217], v129 offset:96
	v_add_f32_e32 v242, v44, v242
	v_add_f32_e32 v243, v45, v243
	v_add_f32_e32 v242, v46, v242
	v_add_f32_e32 v243, v47, v243
	v_cvt_pk_bf16_f32 v32, v32, v33
	v_cvt_pk_bf16_f32 v33, v34, v35
	v_cvt_pk_bf16_f32 v34, v36, v37
	v_cvt_pk_bf16_f32 v35, v38, v39
	v_cvt_pk_bf16_f32 v36, v40, v41
	v_cvt_pk_bf16_f32 v37, v42, v43
	v_cvt_pk_bf16_f32 v38, v44, v45
	v_cvt_pk_bf16_f32 v39, v46, v47
	v_add_f32_e32 v242, v242, v243
	v_fmac_f32_e32 v242, v182, v238
	v_mfma_f32_32x32x16_bf16 v[16:31], v[218:221], v[32:35], v[16:31]
	ds_read_b128 v[218:221], v129 offset:4608
	v_mfma_f32_32x32x16_bf16 v[16:31], v[222:225], v[36:39], v[16:31]
	ds_read_b128 v[222:225], v129 offset:4640
	v_mfma_f32_32x32x16_bf16 v[0:15], v[226:229], v[32:35], v[0:15]
	ds_read_b128 v[226:229], v129 offset:4672
	v_mfma_f32_32x32x16_bf16 v[0:15], v[230:233], v[36:39], v[0:15]
	ds_read_b128 v[230:233], v129 offset:4704
	v_mov_b32_e32 v182, v242
	v_mov_b32_e32 v183, v236
	v_add_u32_e32 v129, 0x2400, v129
	v_add_u32_e32 v234, 0x3000, v234
	s_add_i32 s19, s19, 64
	v_subrev_u32_e32 v179, 64, v179
	v_add_u32_e32 v180, 64, v180
	s_add_i32 s21, s21, -1
	s_cmp_lg_u32 s21, 0
	s_cbranch_scc1 .Llat1_top
	v_mov_b32_e32 v54, v182
	v_mov_b32_e32 v156, v183
	s_branch .LBB0_387

.LBB0_389:
	s_andn2_b64 vcc, exec, s[4:5]
	s_cbranch_vccnz .LBB0_393
	s_movk_i32 s6, 0x90
	v_mad_u64_u32 v[32:33], s[4:5], v148, s6, v[146:147]
	s_barrier
	v_mad_u32_u24 v32, v148, s6, v146
	ds_write_b96 v32, v[112:114]
	ds_write_b32 v32, v149 offset:12
	v_mul_u32_u24_e32 v33, 0xc0, v148
	v_add_u32_e32 v33, v33, v146
	ds_write_b128 v33, v[160:163] offset:46080
	v_mad_u32_u24 v32, v150, s6, v146
	ds_write_b96 v32, v[116:118]
	ds_write_b32 v32, v153 offset:12
	v_mul_u32_u24_e32 v33, 0xc0, v150
	v_add_u32_e32 v33, v33, v146
	ds_write_b128 v33, v[164:167] offset:46080
	v_mad_u32_u24 v32, v152, s6, v146
	ds_write_b96 v32, v[120:122]
	ds_write_b32 v32, v176 offset:12
	v_mul_u32_u24_e32 v33, 0xc0, v152
	v_add_u32_e32 v33, v33, v146
	ds_write_b128 v33, v[168:171] offset:46080
	v_mad_u32_u24 v32, v154, s6, v146
	ds_write_b96 v32, v[124:126]
	ds_write_b32 v32, v177 offset:12
	v_mul_u32_u24_e32 v33, 0xc0, v154
	v_add_u32_e32 v33, v33, v146
	ds_write_b128 v33, v[172:175] offset:46080
	v_and_b32_e32 v32, 64, v251
	v_xor_b32_e32 v155, 32, v251
	v_add_u32_e32 v173, 64, v32
	v_cmp_lt_i32_e32 vcc, v155, v173
	s_movk_i32 s2, 0x90
	s_mov_b32 s4, 0
	v_cndmask_b32_e32 v32, v251, v155, vcc
	v_lshlrev_b32_e32 v113, 2, v32
	s_waitcnt lgkmcnt(0)
	s_barrier
	v_mov_b32_e32 v244, v54
	s_mov_b32 s21, 4
	v_mov_b32_e32 v234, v235
	ds_read_b128 v[202:205], v127
	ds_read_b128 v[206:209], v127 offset:32
	ds_read_b128 v[210:213], v127 offset:64
	ds_read_b128 v[214:217], v127 offset:96
	ds_read_b128 v[218:221], v127 offset:4608
	ds_read_b128 v[222:225], v127 offset:4640
	ds_read_b128 v[226:229], v127 offset:4672
	ds_read_b128 v[230:233], v127 offset:4704
	v_add_u32_e32 v127, 0x2400, v127
.Llat2_top:
	s_waitcnt lgkmcnt(7)
	v_mfma_f32_32x32x16_bf16 v[48:63], v[202:205], v[96:99], 0
	ds_read_b64_tr_b16 v[202:203], v234 offset:46080
	ds_read_b64_tr_b16 v[204:205], v234 offset:47616
	s_waitcnt lgkmcnt(8)
	v_mfma_f32_32x32x16_bf16 v[48:63], v[206:209], v[100:103], v[48:63]
	ds_read_b64_tr_b16 v[206:207], v234 offset:49152
	ds_read_b64_tr_b16 v[208:209], v234 offset:50688
	s_waitcnt lgkmcnt(9)
	v_mfma_f32_32x32x16_bf16 v[48:63], v[210:213], v[104:107], v[48:63]
	ds_read_b64_tr_b16 v[210:211], v234 offset:46144
	ds_read_b64_tr_b16 v[212:213], v234 offset:47680
	s_waitcnt lgkmcnt(10)
	v_mfma_f32_32x32x16_bf16 v[48:63], v[214:217], v[108:111], v[48:63]
	ds_read_b64_tr_b16 v[214:215], v234 offset:49216
	ds_read_b64_tr_b16 v[216:217], v234 offset:50752
	s_waitcnt lgkmcnt(11)
	v_mfma_f32_32x32x16_bf16 v[32:47], v[218:221], v[96:99], 0
	ds_read_b64_tr_b16 v[218:219], v234 offset:52224
	ds_read_b64_tr_b16 v[220:221], v234 offset:53760
	s_waitcnt lgkmcnt(12)
	v_mfma_f32_32x32x16_bf16 v[32:47], v[222:225], v[100:103], v[32:47]
	ds_read_b64_tr_b16 v[222:223], v234 offset:55296
	ds_read_b64_tr_b16 v[224:225], v234 offset:56832
	s_waitcnt lgkmcnt(13)
	v_mfma_f32_32x32x16_bf16 v[32:47], v[226:229], v[104:107], v[32:47]
	ds_read_b64_tr_b16 v[226:227], v234 offset:52288
	ds_read_b64_tr_b16 v[228:229], v234 offset:53824
	s_waitcnt lgkmcnt(13)
	v_mfma_f32_32x32x16_bf16 v[32:47], v[230:233], v[108:111], v[32:47]
	ds_read_b64_tr_b16 v[230:231], v234 offset:55360
	ds_read_b64_tr_b16 v[232:233], v234 offset:56896
	v_max3_f32 v236, v48, s16, v49
	v_max3_f32 v236, v236, v50, v51
	v_max3_f32 v236, v236, v52, v53
	v_max3_f32 v236, v236, v54, v55
	v_max3_f32 v236, v236, v56, v57
	v_max3_f32 v236, v236, v58, v59
	v_max3_f32 v236, v236, v60, v61
	v_max3_f32 v236, v236, v62, v63
	s_nop 3
	v_max3_f32 v236, v236, v32, v33
	v_max3_f32 v236, v236, v34, v35
	v_max3_f32 v236, v236, v36, v37
	v_max3_f32 v236, v236, v38, v39
	v_max3_f32 v236, v236, v40, v41
	v_max3_f32 v236, v236, v42, v43
	v_max3_f32 v236, v236, v44, v45
	v_max3_f32 v236, v236, v46, v47
	ds_bpermute_b32 v237, v113, v236
	s_waitcnt lgkmcnt(0)
	v_max3_f32 v236, v156, v236, v237
	v_sub_f32_e32 v238, v156, v236
	v_sub_f32_e32 v48, v48, v236
	v_sub_f32_e32 v49, v49, v236
	v_sub_f32_e32 v50, v50, v236
	v_sub_f32_e32 v51, v51, v236
	v_sub_f32_e32 v52, v52, v236
	v_sub_f32_e32 v53, v53, v236
	v_sub_f32_e32 v54, v54, v236
	v_sub_f32_e32 v55, v55, v236
	v_sub_f32_e32 v56, v56, v236
	v_sub_f32_e32 v57, v57, v236
	v_sub_f32_e32 v58, v58, v236
	v_sub_f32_e32 v59, v59, v236
	v_sub_f32_e32 v60, v60, v236
	v_sub_f32_e32 v61, v61, v236
	v_sub_f32_e32 v62, v62, v236
	v_sub_f32_e32 v63, v63, v236
	v_exp_f32_e32 v238, v238
	v_exp_f32_e32 v48, v48
	v_exp_f32_e32 v49, v49
	v_exp_f32_e32 v50, v50
	v_exp_f32_e32 v51, v51
	v_exp_f32_e32 v52, v52
	v_exp_f32_e32 v53, v53
	v_exp_f32_e32 v54, v54
	v_exp_f32_e32 v55, v55
	v_exp_f32_e32 v56, v56
	v_exp_f32_e32 v57, v57
	v_exp_f32_e32 v58, v58
	v_exp_f32_e32 v59, v59
	v_exp_f32_e32 v60, v60
	v_exp_f32_e32 v61, v61
	v_exp_f32_e32 v62, v62
	v_exp_f32_e32 v63, v63
	v_add_f32_e32 v242, 0, v48
	v_add_f32_e32 v243, 0, v49
	v_add_f32_e32 v242, v50, v242
	v_add_f32_e32 v243, v51, v243
	v_add_f32_e32 v242, v52, v242
	v_add_f32_e32 v243, v53, v243
	v_add_f32_e32 v242, v54, v242
	v_add_f32_e32 v243, v55, v243
	v_add_f32_e32 v242, v56, v242
	v_add_f32_e32 v243, v57, v243
	v_add_f32_e32 v242, v58, v242
	v_add_f32_e32 v243, v59, v243
	v_add_f32_e32 v242, v60, v242
	v_add_f32_e32 v243, v61, v243
	v_add_f32_e32 v242, v62, v242
	v_add_f32_e32 v243, v63, v243
	v_cvt_pk_bf16_f32 v48, v48, v49
	v_cvt_pk_bf16_f32 v49, v50, v51
	v_cvt_pk_bf16_f32 v50, v52, v53
	v_cvt_pk_bf16_f32 v51, v54, v55
	v_cvt_pk_bf16_f32 v52, v56, v57
	v_cvt_pk_bf16_f32 v53, v58, v59
	v_cvt_pk_bf16_f32 v54, v60, v61
	v_cvt_pk_bf16_f32 v55, v62, v63
	v_mul_f32_e32 v16, v16, v238
	v_mul_f32_e32 v17, v17, v238
	v_mul_f32_e32 v18, v18, v238
	v_mul_f32_e32 v19, v19, v238
	v_mul_f32_e32 v20, v20, v238
	v_mul_f32_e32 v21, v21, v238
	v_mul_f32_e32 v22, v22, v238
	v_mul_f32_e32 v23, v23, v238
	v_mul_f32_e32 v24, v24, v238
	v_mul_f32_e32 v25, v25, v238
	v_mul_f32_e32 v26, v26, v238
	v_mul_f32_e32 v27, v27, v238
	v_mul_f32_e32 v28, v28, v238
	v_mul_f32_e32 v29, v29, v238
	v_mul_f32_e32 v30, v30, v238
	v_mul_f32_e32 v31, v31, v238
	v_mul_f32_e32 v0, v0, v238
	v_mul_f32_e32 v1, v1, v238
	v_mul_f32_e32 v2, v2, v238
	v_mul_f32_e32 v3, v3, v238
	v_mul_f32_e32 v4, v4, v238
	v_mul_f32_e32 v5, v5, v238
	v_mul_f32_e32 v6, v6, v238
	v_mul_f32_e32 v7, v7, v238
	v_mul_f32_e32 v8, v8, v238
	v_mul_f32_e32 v9, v9, v238
	v_mul_f32_e32 v10, v10, v238
	v_mul_f32_e32 v11, v11, v238
	v_mul_f32_e32 v12, v12, v238
	v_mul_f32_e32 v13, v13, v238
	v_mul_f32_e32 v14, v14, v238
	v_mul_f32_e32 v15, v15, v238
	v_mfma_f32_32x32x16_bf16 v[16:31], v[202:205], v[48:51], v[16:31]
	ds_read_b128 v[202:205], v127
	v_sub_f32_e32 v32, v32, v236
	v_sub_f32_e32 v33, v33, v236
	v_sub_f32_e32 v34, v34, v236
	v_sub_f32_e32 v35, v35, v236
	v_sub_f32_e32 v36, v36, v236
	v_sub_f32_e32 v37, v37, v236
	v_sub_f32_e32 v38, v38, v236
	v_sub_f32_e32 v39, v39, v236
	v_sub_f32_e32 v40, v40, v236
	v_sub_f32_e32 v41, v41, v236
	v_sub_f32_e32 v42, v42, v236
	v_sub_f32_e32 v43, v43, v236
	v_sub_f32_e32 v44, v44, v236
	v_sub_f32_e32 v45, v45, v236
	v_sub_f32_e32 v46, v46, v236
	v_sub_f32_e32 v47, v47, v236
	v_exp_f32_e32 v32, v32
	v_exp_f32_e32 v33, v33
	v_mfma_f32_32x32x16_bf16 v[16:31], v[206:209], v[52:55], v[16:31]
	ds_read_b128 v[206:209], v127 offset:32
	v_exp_f32_e32 v34, v34
	v_exp_f32_e32 v35, v35
	v_exp_f32_e32 v36, v36
	v_exp_f32_e32 v37, v37
	v_exp_f32_e32 v38, v38
	v_exp_f32_e32 v39, v39
	v_exp_f32_e32 v40, v40
	v_exp_f32_e32 v41, v41
	v_exp_f32_e32 v42, v42
	v_exp_f32_e32 v43, v43
	v_mfma_f32_32x32x16_bf16 v[0:15], v[210:213], v[48:51], v[0:15]
	ds_read_b128 v[210:213], v127 offset:64
	v_exp_f32_e32 v44, v44
	v_exp_f32_e32 v45, v45
	v_exp_f32_e32 v46, v46
	v_exp_f32_e32 v47, v47
	v_add_f32_e32 v242, v32, v242
	v_add_f32_e32 v243, v33, v243
	v_add_f32_e32 v242, v34, v242
	v_add_f32_e32 v243, v35, v243
	v_add_f32_e32 v242, v36, v242
	v_add_f32_e32 v243, v37, v243
	v_add_f32_e32 v242, v38, v242
	v_add_f32_e32 v243, v39, v243
	v_add_f32_e32 v242, v40, v242
	v_add_f32_e32 v243, v41, v243
	v_add_f32_e32 v242, v42, v242
	v_add_f32_e32 v243, v43, v243
	v_mfma_f32_32x32x16_bf16 v[0:15], v[214:217], v[52:55], v[0:15]
	ds_read_b128 v[214:217], v127 offset:96
	v_add_f32_e32 v242, v44, v242
	v_add_f32_e32 v243, v45, v243
	v_add_f32_e32 v242, v46, v242
	v_add_f32_e32 v243, v47, v243
	v_cvt_pk_bf16_f32 v32, v32, v33
	v_cvt_pk_bf16_f32 v33, v34, v35
	v_cvt_pk_bf16_f32 v34, v36, v37
	v_cvt_pk_bf16_f32 v35, v38, v39
	v_cvt_pk_bf16_f32 v36, v40, v41
	v_cvt_pk_bf16_f32 v37, v42, v43
	v_cvt_pk_bf16_f32 v38, v44, v45
	v_cvt_pk_bf16_f32 v39, v46, v47
	v_add_f32_e32 v242, v242, v243
	v_fmac_f32_e32 v242, v244, v238
	v_mfma_f32_32x32x16_bf16 v[16:31], v[218:221], v[32:35], v[16:31]
	ds_read_b128 v[218:221], v127 offset:4608
	v_mfma_f32_32x32x16_bf16 v[16:31], v[222:225], v[36:39], v[16:31]
	ds_read_b128 v[222:225], v127 offset:4640
	v_mfma_f32_32x32x16_bf16 v[0:15], v[226:229], v[32:35], v[0:15]
	ds_read_b128 v[226:229], v127 offset:4672
	v_mfma_f32_32x32x16_bf16 v[0:15], v[230:233], v[36:39], v[0:15]
	ds_read_b128 v[230:233], v127 offset:4704
	v_mov_b32_e32 v244, v242
	v_mov_b32_e32 v156, v236
	v_add_u32_e32 v127, 0x2400, v127
	v_add_u32_e32 v234, 0x3000, v234
	s_add_i32 s21, s21, -1
	s_cmp_lg_u32 s21, 0
	s_cbranch_scc1 .Llat2_top
	v_mov_b32_e32 v54, v244
	v_mov_b32_e32 v32, v251

.LBB0_430:
	s_and_b64 vcc, exec, s[0:1]
	s_cbranch_vccz .LBB0_444
	s_mov_b64 s[0:1], 0x697b000
	s_mov_b64 s[6:7], 0x9f7b000
	s_mov_b64 s[4:5], 0xb83b000
	v_mbcnt_lo_u32_b32 v19, -1, 0
	v_mbcnt_hi_u32_b32 v19, -1, v19
	s_add_u32 s0, s28, s0
	v_add_u32_e32 v26, s3, v19
	v_ashrrev_i32_e32 v27, 3, v26
	s_addc_u32 s1, s29, s1
	v_readlane_b32 s10, v254, 62
	v_readlane_b32 s8, v254, 60
	v_and_b32_e32 v30, 7, v19
	v_lshlrev_b32_e32 v18, 4, v30
	s_lshl_b32 s68, s8, 1
	s_waitcnt lgkmcnt(0)
	v_add_u32_e32 v33, s10, v27
	v_mov_b64_e32 v[34:35], s[0:1]
	v_mad_i64_i32 v[34:35], s[10:11], v33, s62, v[34:35]
	v_lshlrev_b32_e32 v33, 4, v19
	v_lshl_add_u64 v[34:35], v[34:35], 0, s[68:69]
	v_and_b32_e32 v198, 0x70, v33
	v_lshl_add_u64 v[38:39], v[34:35], 0, v[198:199]
	s_mov_b64 s[8:9], 0x48000
	v_lshl_add_u64 v[40:41], v[38:39], 0, s[8:9]
	v_lshl_add_u64 v[42:43], v[40:41], 0, s[8:9]
	v_lshl_add_u64 v[44:45], v[42:43], 0, s[8:9]
	global_load_dwordx4 v[202:205], v[38:39], off offset:1024
	global_load_dwordx4 v[218:221], v[38:39], off offset:1280
	global_load_dwordx4 v[206:209], v[40:41], off offset:1024
	global_load_dwordx4 v[222:225], v[40:41], off offset:1280
	global_load_dwordx4 v[210:213], v[42:43], off offset:1024
	global_load_dwordx4 v[226:229], v[42:43], off offset:1280
	global_load_dwordx4 v[214:217], v[44:45], off offset:1024
	global_load_dwordx4 v[230:233], v[44:45], off offset:1280
	s_movk_i32 s8, 0x1430
	v_mad_u32_u24 v30, v30, s8, v18
	v_lshrrev_b32_e32 v0, 6, v26
	v_readlane_b32 s8, v254, 61
	v_and_b32_e32 v6, 31, v19
	v_and_b32_e32 v1, 0xffffffe0, v27
	v_and_or_b32 v129, v0, 3, s8
	v_readlane_b32 s8, v254, 63
	v_bfe_u32 v7, v19, 5, 1
	v_lshlrev_b32_e32 v198, 7, v129
	v_or_b32_e32 v0, s8, v6
	v_add_u32_e32 v112, v0, v1
	v_mov_b64_e32 v[0:1], s[0:1]
	v_mad_i64_i32 v[0:1], s[0:1], v112, s62, v[0:1]
	v_lshl_add_u64 v[0:1], v[0:1], 0, v[198:199]
	v_lshlrev_b32_e32 v2, 4, v7
	v_mov_b32_e32 v3, v199
	v_lshl_add_u64 v[4:5], v[0:1], 0, v[2:3]
	v_lshlrev_b32_e32 v198, 3, v7
	global_load_dwordx4 v[96:99], v[4:5], off
	global_load_dwordx4 v[100:103], v[4:5], off offset:32
	global_load_dwordx4 v[104:107], v[4:5], off offset:64
	global_load_dwordx4 v[108:111], v[4:5], off offset:96
	v_lshlrev_b32_e32 v4, 8, v129
	v_mov_b32_e32 v5, v199
	v_lshl_add_u64 v[0:1], v[0:1], 0, v[198:199]
	v_lshl_add_u64 v[4:5], s[90:91], 0, v[4:5]
	v_lshl_add_u64 v[4:5], v[4:5], 0, v[2:3]
	global_load_dwordx2 v[130:131], v[0:1], off offset:1536
	global_load_dwordx4 v[92:95], v[4:5], off
	global_load_dwordx2 v[126:127], v[0:1], off offset:1552
	global_load_dwordx4 v[88:91], v[4:5], off offset:32
	global_load_dwordx2 v[124:125], v[0:1], off offset:1568
	global_load_dwordx4 v[84:87], v[4:5], off offset:64
	global_load_dwordx2 v[122:123], v[0:1], off offset:1584
	global_load_dwordx4 v[80:83], v[4:5], off offset:96
	global_load_dwordx2 v[120:121], v[0:1], off offset:1600
	global_load_dwordx4 v[76:79], v[4:5], off offset:128
	global_load_dwordx2 v[118:119], v[0:1], off offset:1616
	global_load_dwordx4 v[72:75], v[4:5], off offset:160
	global_load_dwordx2 v[116:117], v[0:1], off offset:1632
	global_load_dwordx4 v[68:71], v[4:5], off offset:192
	global_load_dwordx2 v[114:115], v[0:1], off offset:1648
	global_load_dwordx4 v[64:67], v[4:5], off offset:224
	v_readlane_b32 s36, v254, 0
	v_or_b32_e32 v0, s20, v129
	v_mov_b32_e32 v1, v199
	v_readlane_b32 s40, v254, 4
	v_readlane_b32 s41, v254, 5
	v_cmp_eq_u32_e32 vcc, 0, v7
	v_mov_b32_e32 v16, 0
	v_lshl_add_u64 v[0:1], v[0:1], 2, s[40:41]
	global_load_dword v0, v[0:1], off
	s_waitcnt vmcnt(21)
	v_mad_u32_u24 v42, v27, s2, v18
	v_mul_u32_u24_e32 v33, 0xc0, v27
	v_add_u32_e32 v33, v33, v18
	v_add_u32_e32 v33, 0xb400, v33
	ds_write_b128 v42, v[202:205]
	ds_write_b128 v33, v[218:221]
	ds_write_b128 v42, v[206:209] offset:9216
	ds_write_b128 v33, v[222:225] offset:12288
	ds_write_b128 v42, v[210:213] offset:18432
	ds_write_b128 v33, v[226:229] offset:24576
	ds_write_b128 v42, v[214:217] offset:27648
	ds_write_b128 v33, v[230:233] offset:36864
	v_bfe_u32 v34, v19, 2, 2
	v_mul_u32_u24_e32 v235, 0xc0, v34
	v_lshrrev_b32_e32 v34, 5, v19
	v_lshl_add_u32 v235, v34, 8, v235
	v_lshl_add_u32 v235, v34, 9, v235
	v_bfe_u32 v34, v19, 4, 1
	v_lshl_add_u32 v235, v34, 5, v235
	v_and_b32_e32 v34, 3, v19
	v_lshl_add_u32 v235, v34, 3, v235
	v_and_b32_e32 v1, 64, v251
	v_add_u32_e32 v1, 64, v1
	v_ashrrev_i32_e32 v113, 31, v112
	v_lshlrev_b32_e32 v132, 6, v129
	v_lshlrev_b32_e32 v128, 2, v7
	s_mov_b32 s8, 0
	v_cndmask_b32_e64 v48, 0, 1.0, vcc
	v_mad_u32_u24 v136, v6, s2, v2
	v_mov_b32_e32 v17, v16
	v_mov_b32_e32 v18, v16
	v_mov_b32_e32 v19, v16
	v_mov_b32_e32 v20, v16
	v_mov_b32_e32 v21, v16
	v_mov_b32_e32 v22, v16
	v_mov_b32_e32 v23, v16
	v_mov_b32_e32 v24, v16
	v_mov_b32_e32 v25, v16
	v_mov_b32_e32 v26, v16
	v_mov_b32_e32 v27, v16
	v_mov_b32_e32 v28, v16
	v_mov_b32_e32 v29, v16
	v_mov_b32_e32 v30, v16
	v_mov_b32_e32 v31, v16
	v_mov_b32_e32 v2, v16
	v_mov_b32_e32 v3, v16
	v_mov_b32_e32 v4, v16
	v_mov_b32_e32 v5, v16
	v_mov_b32_e32 v7, v16
	v_mov_b32_e32 v8, v16
	v_mov_b32_e32 v9, v16
	v_mov_b32_e32 v10, v16
	v_mov_b32_e32 v11, v16
	v_mov_b32_e32 v12, v16
	v_mov_b32_e32 v13, v16
	v_mov_b32_e32 v14, v16
	v_mov_b32_e32 v15, v16
	v_readlane_b32 s37, v254, 1
	v_readlane_b32 s38, v254, 2
	v_readlane_b32 s39, v254, 3
	v_readlane_b32 s42, v254, 6
	v_readlane_b32 s43, v254, 7
	v_readlane_b32 s44, v254, 8
	v_readlane_b32 s45, v254, 9
	v_readlane_b32 s46, v254, 10
	v_readlane_b32 s47, v254, 11
	v_readlane_b32 s48, v254, 12
	v_readlane_b32 s49, v254, 13
	v_readlane_b32 s50, v254, 14
	v_readlane_b32 s51, v254, 15
	s_waitcnt lgkmcnt(0)
	s_barrier
	s_waitcnt vmcnt(0)
	v_mul_f32_e32 v137, 0x3fb8aa3b, v0
	v_xor_b32_e32 v0, 32, v251
	v_cmp_lt_i32_e64 s[0:1], v0, v1
	v_mov_b32_e32 v1, v16
	s_nop 0
	v_cndmask_b32_e64 v0, v251, v0, s[0:1]
	s_movk_i32 s0, 0x288
	v_lshlrev_b32_e32 v133, 2, v0
	v_mad_u32_u24 v135, v6, s0, v198
	v_mov_b32_e32 v0, v16
	v_mov_b32_e32 v6, v16
	v_mov_b32_e32 v244, v48
	s_mov_b32 s21, 4
	v_mov_b32_e32 v234, v235
	ds_read_b128 v[202:205], v136
	ds_read_b128 v[206:209], v136 offset:32
	ds_read_b128 v[210:213], v136 offset:64
	ds_read_b128 v[214:217], v136 offset:96
	ds_read_b128 v[218:221], v136 offset:4608
	ds_read_b128 v[222:225], v136 offset:4640
	ds_read_b128 v[226:229], v136 offset:4672
	ds_read_b128 v[230:233], v136 offset:4704
	v_add_u32_e32 v136, 0x2400, v136
.Lctx_top:
	s_waitcnt lgkmcnt(7)
	v_mfma_f32_32x32x16_bf16 v[48:63], v[202:205], v[96:99], 0
	ds_read_b64_tr_b16 v[202:203], v234 offset:46080
	ds_read_b64_tr_b16 v[204:205], v234 offset:47616
	s_waitcnt lgkmcnt(8)
	v_mfma_f32_32x32x16_bf16 v[48:63], v[206:209], v[100:103], v[48:63]
	ds_read_b64_tr_b16 v[206:207], v234 offset:49152
	ds_read_b64_tr_b16 v[208:209], v234 offset:50688
	s_waitcnt lgkmcnt(9)
	v_mfma_f32_32x32x16_bf16 v[48:63], v[210:213], v[104:107], v[48:63]
	ds_read_b64_tr_b16 v[210:211], v234 offset:46144
	ds_read_b64_tr_b16 v[212:213], v234 offset:47680
	s_waitcnt lgkmcnt(10)
	v_mfma_f32_32x32x16_bf16 v[48:63], v[214:217], v[108:111], v[48:63]
	ds_read_b64_tr_b16 v[214:215], v234 offset:49216
	ds_read_b64_tr_b16 v[216:217], v234 offset:50752
	s_waitcnt lgkmcnt(11)
	v_mfma_f32_32x32x16_bf16 v[32:47], v[218:221], v[96:99], 0
	ds_read_b64_tr_b16 v[218:219], v234 offset:52224
	ds_read_b64_tr_b16 v[220:221], v234 offset:53760
	s_waitcnt lgkmcnt(12)
	v_mfma_f32_32x32x16_bf16 v[32:47], v[222:225], v[100:103], v[32:47]
	ds_read_b64_tr_b16 v[222:223], v234 offset:55296
	ds_read_b64_tr_b16 v[224:225], v234 offset:56832
	s_waitcnt lgkmcnt(13)
	v_mfma_f32_32x32x16_bf16 v[32:47], v[226:229], v[104:107], v[32:47]
	ds_read_b64_tr_b16 v[226:227], v234 offset:52288
	ds_read_b64_tr_b16 v[228:229], v234 offset:53824
	s_waitcnt lgkmcnt(13)
	v_mfma_f32_32x32x16_bf16 v[32:47], v[230:233], v[108:111], v[32:47]
	ds_read_b64_tr_b16 v[230:231], v234 offset:55360
	ds_read_b64_tr_b16 v[232:233], v234 offset:56896
	v_max3_f32 v236, v48, s16, v49
	v_max3_f32 v236, v236, v50, v51
	v_max3_f32 v236, v236, v52, v53
	v_max3_f32 v236, v236, v54, v55
	v_max3_f32 v236, v236, v56, v57
	v_max3_f32 v236, v236, v58, v59
	v_max3_f32 v236, v236, v60, v61
	v_max3_f32 v236, v236, v62, v63
	s_nop 3
	v_max3_f32 v236, v236, v32, v33
	v_max3_f32 v236, v236, v34, v35
	v_max3_f32 v236, v236, v36, v37
	v_max3_f32 v236, v236, v38, v39
	v_max3_f32 v236, v236, v40, v41
	v_max3_f32 v236, v236, v42, v43
	v_max3_f32 v236, v236, v44, v45
	v_max3_f32 v236, v236, v46, v47
	ds_bpermute_b32 v237, v133, v236
	s_waitcnt lgkmcnt(0)
	v_max3_f32 v236, v137, v236, v237
	v_sub_f32_e32 v238, v137, v236
	v_sub_f32_e32 v48, v48, v236
	v_sub_f32_e32 v49, v49, v236
	v_sub_f32_e32 v50, v50, v236
	v_sub_f32_e32 v51, v51, v236
	v_sub_f32_e32 v52, v52, v236
	v_sub_f32_e32 v53, v53, v236
	v_sub_f32_e32 v54, v54, v236
	v_sub_f32_e32 v55, v55, v236
	v_sub_f32_e32 v56, v56, v236
	v_sub_f32_e32 v57, v57, v236
	v_sub_f32_e32 v58, v58, v236
	v_sub_f32_e32 v59, v59, v236
	v_sub_f32_e32 v60, v60, v236
	v_sub_f32_e32 v61, v61, v236
	v_sub_f32_e32 v62, v62, v236
	v_sub_f32_e32 v63, v63, v236
	v_exp_f32_e32 v238, v238
	v_exp_f32_e32 v48, v48
	v_exp_f32_e32 v49, v49
	v_exp_f32_e32 v50, v50
	v_exp_f32_e32 v51, v51
	v_exp_f32_e32 v52, v52
	v_exp_f32_e32 v53, v53
	v_exp_f32_e32 v54, v54
	v_exp_f32_e32 v55, v55
	v_exp_f32_e32 v56, v56
	v_exp_f32_e32 v57, v57
	v_exp_f32_e32 v58, v58
	v_exp_f32_e32 v59, v59
	v_exp_f32_e32 v60, v60
	v_exp_f32_e32 v61, v61
	v_exp_f32_e32 v62, v62
	v_exp_f32_e32 v63, v63
	v_add_f32_e32 v242, 0, v48
	v_add_f32_e32 v243, 0, v49
	v_add_f32_e32 v242, v50, v242
	v_add_f32_e32 v243, v51, v243
	v_add_f32_e32 v242, v52, v242
	v_add_f32_e32 v243, v53, v243
	v_add_f32_e32 v242, v54, v242
	v_add_f32_e32 v243, v55, v243
	v_add_f32_e32 v242, v56, v242
	v_add_f32_e32 v243, v57, v243
	v_add_f32_e32 v242, v58, v242
	v_add_f32_e32 v243, v59, v243
	v_add_f32_e32 v242, v60, v242
	v_add_f32_e32 v243, v61, v243
	v_add_f32_e32 v242, v62, v242
	v_add_f32_e32 v243, v63, v243
	v_cvt_pk_bf16_f32 v48, v48, v49
	v_cvt_pk_bf16_f32 v49, v50, v51
	v_cvt_pk_bf16_f32 v50, v52, v53
	v_cvt_pk_bf16_f32 v51, v54, v55
	v_cvt_pk_bf16_f32 v52, v56, v57
	v_cvt_pk_bf16_f32 v53, v58, v59
	v_cvt_pk_bf16_f32 v54, v60, v61
	v_cvt_pk_bf16_f32 v55, v62, v63
	v_mul_f32_e32 v16, v16, v238
	v_mul_f32_e32 v17, v17, v238
	v_mul_f32_e32 v18, v18, v238
	v_mul_f32_e32 v19, v19, v238
	v_mul_f32_e32 v20, v20, v238
	v_mul_f32_e32 v21, v21, v238
	v_mul_f32_e32 v22, v22, v238
	v_mul_f32_e32 v23, v23, v238
	v_mul_f32_e32 v24, v24, v238
	v_mul_f32_e32 v25, v25, v238
	v_mul_f32_e32 v26, v26, v238
	v_mul_f32_e32 v27, v27, v238
	v_mul_f32_e32 v28, v28, v238
	v_mul_f32_e32 v29, v29, v238
	v_mul_f32_e32 v30, v30, v238
	v_mul_f32_e32 v31, v31, v238
	v_mul_f32_e32 v0, v0, v238
	v_mul_f32_e32 v1, v1, v238
	v_mul_f32_e32 v2, v2, v238
	v_mul_f32_e32 v3, v3, v238
	v_mul_f32_e32 v4, v4, v238
	v_mul_f32_e32 v5, v5, v238
	v_mul_f32_e32 v6, v6, v238
	v_mul_f32_e32 v7, v7, v238
	v_mul_f32_e32 v8, v8, v238
	v_mul_f32_e32 v9, v9, v238
	v_mul_f32_e32 v10, v10, v238
	v_mul_f32_e32 v11, v11, v238
	v_mul_f32_e32 v12, v12, v238
	v_mul_f32_e32 v13, v13, v238
	v_mul_f32_e32 v14, v14, v238
	v_mul_f32_e32 v15, v15, v238
	v_mfma_f32_32x32x16_bf16 v[16:31], v[202:205], v[48:51], v[16:31]
	ds_read_b128 v[202:205], v136
	v_sub_f32_e32 v32, v32, v236
	v_sub_f32_e32 v33, v33, v236
	v_sub_f32_e32 v34, v34, v236
	v_sub_f32_e32 v35, v35, v236
	v_sub_f32_e32 v36, v36, v236
	v_sub_f32_e32 v37, v37, v236
	v_sub_f32_e32 v38, v38, v236
	v_sub_f32_e32 v39, v39, v236
	v_sub_f32_e32 v40, v40, v236
	v_sub_f32_e32 v41, v41, v236
	v_sub_f32_e32 v42, v42, v236
	v_sub_f32_e32 v43, v43, v236
	v_sub_f32_e32 v44, v44, v236
	v_sub_f32_e32 v45, v45, v236
	v_sub_f32_e32 v46, v46, v236
	v_sub_f32_e32 v47, v47, v236
	v_exp_f32_e32 v32, v32
	v_exp_f32_e32 v33, v33
	v_mfma_f32_32x32x16_bf16 v[16:31], v[206:209], v[52:55], v[16:31]
	ds_read_b128 v[206:209], v136 offset:32
	v_exp_f32_e32 v34, v34
	v_exp_f32_e32 v35, v35
	v_exp_f32_e32 v36, v36
	v_exp_f32_e32 v37, v37
	v_exp_f32_e32 v38, v38
	v_exp_f32_e32 v39, v39
	v_exp_f32_e32 v40, v40
	v_exp_f32_e32 v41, v41
	v_exp_f32_e32 v42, v42
	v_exp_f32_e32 v43, v43
	v_mfma_f32_32x32x16_bf16 v[0:15], v[210:213], v[48:51], v[0:15]
	ds_read_b128 v[210:213], v136 offset:64
	v_exp_f32_e32 v44, v44
	v_exp_f32_e32 v45, v45
	v_exp_f32_e32 v46, v46
	v_exp_f32_e32 v47, v47
	v_add_f32_e32 v242, v32, v242
	v_add_f32_e32 v243, v33, v243
	v_add_f32_e32 v242, v34, v242
	v_add_f32_e32 v243, v35, v243
	v_add_f32_e32 v242, v36, v242
	v_add_f32_e32 v243, v37, v243
	v_add_f32_e32 v242, v38, v242
	v_add_f32_e32 v243, v39, v243
	v_add_f32_e32 v242, v40, v242
	v_add_f32_e32 v243, v41, v243
	v_add_f32_e32 v242, v42, v242
	v_add_f32_e32 v243, v43, v243
	v_mfma_f32_32x32x16_bf16 v[0:15], v[214:217], v[52:55], v[0:15]
	ds_read_b128 v[214:217], v136 offset:96
	v_add_f32_e32 v242, v44, v242
	v_add_f32_e32 v243, v45, v243
	v_add_f32_e32 v242, v46, v242
	v_add_f32_e32 v243, v47, v243
	v_cvt_pk_bf16_f32 v32, v32, v33
	v_cvt_pk_bf16_f32 v33, v34, v35
	v_cvt_pk_bf16_f32 v34, v36, v37
	v_cvt_pk_bf16_f32 v35, v38, v39
	v_cvt_pk_bf16_f32 v36, v40, v41
	v_cvt_pk_bf16_f32 v37, v42, v43
	v_cvt_pk_bf16_f32 v38, v44, v45
	v_cvt_pk_bf16_f32 v39, v46, v47
	v_add_f32_e32 v242, v242, v243
	v_fmac_f32_e32 v242, v244, v238
	v_mfma_f32_32x32x16_bf16 v[16:31], v[218:221], v[32:35], v[16:31]
	ds_read_b128 v[218:221], v136 offset:4608
	v_mfma_f32_32x32x16_bf16 v[16:31], v[222:225], v[36:39], v[16:31]
	ds_read_b128 v[222:225], v136 offset:4640
	v_mfma_f32_32x32x16_bf16 v[0:15], v[226:229], v[32:35], v[0:15]
	ds_read_b128 v[226:229], v136 offset:4672
	v_mfma_f32_32x32x16_bf16 v[0:15], v[230:233], v[36:39], v[0:15]
	ds_read_b128 v[230:233], v136 offset:4704
	v_mov_b32_e32 v244, v242
	v_mov_b32_e32 v137, v236
	v_add_u32_e32 v136, 0x2400, v136
	v_add_u32_e32 v234, 0x3000, v234
	s_add_i32 s21, s21, -1
	s_cmp_lg_u32 s21, 0
	s_cbranch_scc1 .Lctx_top
	v_mov_b32_e32 v48, v244
	ds_bpermute_b32 v32, v133, v48
	s_add_u32 s0, s28, s6
	s_addc_u32 s1, s29, s7
	v_lshlrev_b64 v[34:35], 11, v[112:113]
	v_lshl_add_u64 v[34:35], s[0:1], 0, v[34:35]
	s_waitcnt lgkmcnt(0)
	v_add_f32_e32 v32, v48, v32
	v_rcp_f32_e32 v32, v32
	v_lshlrev_b32_e32 v198, 1, v132
	v_lshl_add_u64 v[36:37], v[34:35], 0, v[198:199]
	v_lshlrev_b32_e32 v34, 16, v130
	v_pk_mul_f32 v[38:39], v[16:17], v[32:33] op_sel_hi:[1,0]
	v_mul_f32_e32 v33, 0xbfb8aa3b, v34
	v_exp_f32_e32 v33, v33
	v_and_b32_e32 v35, 0xffff0000, v130
	v_pk_mul_f32 v[16:17], v[38:39], v[38:39]
	v_pk_mul_f32 v[38:39], v[92:93], v[38:39]
	v_add_f32_e32 v33, 1.0, v33
	v_rcp_f32_e32 v40, v33
	v_mul_f32_e32 v33, 0xbfb8aa3b, v35
	v_exp_f32_e32 v33, v33
	v_lshlrev_b32_e32 v198, 1, v128
	v_add_f32_e32 v16, v16, v17
	v_add_f32_e32 v33, 1.0, v33
	v_rcp_f32_e32 v41, v33
	v_pk_mul_f32 v[18:19], v[18:19], v[32:33] op_sel_hi:[1,0]
	v_pk_mul_f32 v[34:35], v[40:41], v[34:35]
	v_lshlrev_b32_e32 v40, 16, v131
	v_mul_f32_e32 v33, 0xbfb8aa3b, v40
	v_exp_f32_e32 v33, v33
	v_and_b32_e32 v41, 0xffff0000, v131
	v_pk_mul_f32 v[34:35], v[34:35], v[38:39]
	v_add_f32_e32 v33, 1.0, v33
	v_rcp_f32_e32 v42, v33
	v_mul_f32_e32 v33, 0xbfb8aa3b, v41
	v_exp_f32_e32 v33, v33
	v_cvt_pk_bf16_f32 v38, v34, v35
	v_pk_mul_f32 v[34:35], v[18:19], v[18:19]
	v_pk_mul_f32 v[18:19], v[94:95], v[18:19]
	v_add_f32_e32 v33, 1.0, v33
	v_rcp_f32_e32 v43, v33
	s_nop 0
	v_pk_mul_f32 v[40:41], v[42:43], v[40:41]
	s_nop 0
	v_pk_mul_f32 v[18:19], v[40:41], v[18:19]
	s_nop 0
	v_cvt_pk_bf16_f32 v39, v18, v19
	v_lshl_add_u64 v[18:19], v[36:37], 0, v[198:199]
	v_lshlrev_b32_e32 v36, 16, v126
	global_store_dwordx2 v[18:19], v[38:39], off
	v_pk_mul_f32 v[38:39], v[20:21], v[32:33] op_sel_hi:[1,0]
	v_mul_f32_e32 v33, 0xbfb8aa3b, v36
	v_exp_f32_e32 v33, v33
	v_and_b32_e32 v37, 0xffff0000, v126
	v_pk_mul_f32 v[20:21], v[38:39], v[38:39]
	v_pk_mul_f32 v[38:39], v[88:89], v[38:39]
	v_add_f32_e32 v33, 1.0, v33
	v_rcp_f32_e32 v40, v33
	v_mul_f32_e32 v33, 0xbfb8aa3b, v37
	v_exp_f32_e32 v33, v33
	v_add_f32_e32 v20, v20, v21
	v_add_f32_e32 v21, v34, v35
	v_add_f32_e32 v16, v16, v21
	v_add_f32_e32 v33, 1.0, v33
	v_rcp_f32_e32 v41, v33
	s_nop 0
	v_pk_mul_f32 v[36:37], v[40:41], v[36:37]
	s_nop 0
	v_pk_mul_f32 v[36:37], v[36:37], v[38:39]
	v_lshlrev_b32_e32 v38, 16, v127
	v_pk_mul_f32 v[40:41], v[22:23], v[32:33] op_sel_hi:[1,0]
	v_mul_f32_e32 v33, 0xbfb8aa3b, v38
	v_exp_f32_e32 v33, v33
	v_and_b32_e32 v39, 0xffff0000, v127
	v_pk_mul_f32 v[22:23], v[40:41], v[40:41]
	v_pk_mul_f32 v[40:41], v[90:91], v[40:41]
	v_add_f32_e32 v33, 1.0, v33
	v_rcp_f32_e32 v42, v33
	v_mul_f32_e32 v33, 0xbfb8aa3b, v39
	v_exp_f32_e32 v33, v33
	v_cvt_pk_bf16_f32 v36, v36, v37
	v_add_f32_e32 v22, v22, v23
	v_add_f32_e32 v20, v20, v22
	v_add_f32_e32 v33, 1.0, v33
	v_rcp_f32_e32 v43, v33
	v_add_f32_e32 v16, v16, v20
	v_pk_mul_f32 v[38:39], v[42:43], v[38:39]
	s_nop 0
	v_pk_mul_f32 v[38:39], v[38:39], v[40:41]
	s_nop 0
	v_cvt_pk_bf16_f32 v37, v38, v39
	global_store_dwordx2 v[18:19], v[36:37], off offset:16
	v_lshlrev_b32_e32 v36, 16, v124
	v_pk_mul_f32 v[38:39], v[24:25], v[32:33] op_sel_hi:[1,0]
	v_mul_f32_e32 v33, 0xbfb8aa3b, v36
	v_exp_f32_e32 v33, v33
	v_and_b32_e32 v37, 0xffff0000, v124
	v_pk_mul_f32 v[24:25], v[38:39], v[38:39]
	v_pk_mul_f32 v[38:39], v[84:85], v[38:39]
	v_add_f32_e32 v33, 1.0, v33
	v_rcp_f32_e32 v40, v33
	v_mul_f32_e32 v33, 0xbfb8aa3b, v37
	v_exp_f32_e32 v33, v33
	v_add_f32_e32 v24, v24, v25
	v_add_f32_e32 v33, 1.0, v33
	v_rcp_f32_e32 v41, v33
	s_nop 0
	v_pk_mul_f32 v[36:37], v[40:41], v[36:37]
	s_nop 0
	v_pk_mul_f32 v[36:37], v[36:37], v[38:39]
	v_lshlrev_b32_e32 v38, 16, v125
	v_pk_mul_f32 v[40:41], v[26:27], v[32:33] op_sel_hi:[1,0]
	v_mul_f32_e32 v33, 0xbfb8aa3b, v38
	v_exp_f32_e32 v33, v33
	v_and_b32_e32 v39, 0xffff0000, v125
	v_pk_mul_f32 v[26:27], v[40:41], v[40:41]
	v_pk_mul_f32 v[40:41], v[86:87], v[40:41]
	v_add_f32_e32 v33, 1.0, v33
	v_rcp_f32_e32 v42, v33
	v_mul_f32_e32 v33, 0xbfb8aa3b, v39
	v_exp_f32_e32 v33, v33
	v_cvt_pk_bf16_f32 v36, v36, v37
	v_add_f32_e32 v33, 1.0, v33
	v_rcp_f32_e32 v43, v33
	s_nop 0
	v_pk_mul_f32 v[38:39], v[42:43], v[38:39]
	s_nop 0
	v_pk_mul_f32 v[38:39], v[38:39], v[40:41]
	s_nop 0
	v_cvt_pk_bf16_f32 v37, v38, v39
	global_store_dwordx2 v[18:19], v[36:37], off offset:32
	v_lshlrev_b32_e32 v36, 16, v122
	v_pk_mul_f32 v[38:39], v[28:29], v[32:33] op_sel_hi:[1,0]
	v_mul_f32_e32 v33, 0xbfb8aa3b, v36
	v_exp_f32_e32 v33, v33
	v_and_b32_e32 v37, 0xffff0000, v122
	v_pk_mul_f32 v[28:29], v[38:39], v[38:39]
	v_pk_mul_f32 v[38:39], v[80:81], v[38:39]
	v_add_f32_e32 v33, 1.0, v33
	v_rcp_f32_e32 v40, v33
	v_mul_f32_e32 v33, 0xbfb8aa3b, v37
	v_exp_f32_e32 v33, v33
	v_add_f32_e32 v17, v28, v29
	v_add_f32_e32 v33, 1.0, v33
	v_rcp_f32_e32 v41, v33
	s_nop 0
	v_pk_mul_f32 v[36:37], v[40:41], v[36:37]
	s_nop 0
	v_pk_mul_f32 v[36:37], v[36:37], v[38:39]
	v_lshlrev_b32_e32 v38, 16, v123
	v_pk_mul_f32 v[40:41], v[30:31], v[32:33] op_sel_hi:[1,0]
	v_mul_f32_e32 v33, 0xbfb8aa3b, v38
	v_exp_f32_e32 v33, v33
	v_and_b32_e32 v39, 0xffff0000, v123
	v_pk_mul_f32 v[30:31], v[40:41], v[40:41]
	v_pk_mul_f32 v[40:41], v[82:83], v[40:41]
	v_add_f32_e32 v33, 1.0, v33
	v_rcp_f32_e32 v42, v33
	v_mul_f32_e32 v33, 0xbfb8aa3b, v39
	v_exp_f32_e32 v33, v33
	v_cvt_pk_bf16_f32 v36, v36, v37
	v_add_f32_e32 v33, 1.0, v33
	v_rcp_f32_e32 v43, v33
	s_nop 0
	v_pk_mul_f32 v[38:39], v[42:43], v[38:39]
	s_nop 0
	v_pk_mul_f32 v[38:39], v[38:39], v[40:41]
	s_nop 0
	v_cvt_pk_bf16_f32 v37, v38, v39
	global_store_dwordx2 v[18:19], v[36:37], off offset:48
	v_lshlrev_b32_e32 v36, 16, v120
	v_pk_mul_f32 v[38:39], v[0:1], v[32:33] op_sel_hi:[1,0]
	v_mul_f32_e32 v33, 0xbfb8aa3b, v36
	v_exp_f32_e32 v33, v33
	v_and_b32_e32 v37, 0xffff0000, v120
	v_pk_mul_f32 v[0:1], v[38:39], v[38:39]
	v_pk_mul_f32 v[38:39], v[76:77], v[38:39]
	v_add_f32_e32 v33, 1.0, v33
	v_rcp_f32_e32 v40, v33
	v_mul_f32_e32 v33, 0xbfb8aa3b, v37
	v_exp_f32_e32 v33, v33
	v_add_f32_e32 v0, v0, v1
	v_add_f32_e32 v33, 1.0, v33
	v_rcp_f32_e32 v41, v33
	s_nop 0
	v_pk_mul_f32 v[36:37], v[40:41], v[36:37]
	s_nop 0
	v_pk_mul_f32 v[36:37], v[36:37], v[38:39]
	v_lshlrev_b32_e32 v38, 16, v121
	v_pk_mul_f32 v[40:41], v[2:3], v[32:33] op_sel_hi:[1,0]
	v_mul_f32_e32 v33, 0xbfb8aa3b, v38
	v_exp_f32_e32 v33, v33
	v_and_b32_e32 v39, 0xffff0000, v121
	v_pk_mul_f32 v[2:3], v[40:41], v[40:41]
	v_pk_mul_f32 v[40:41], v[78:79], v[40:41]
	v_add_f32_e32 v33, 1.0, v33
	v_rcp_f32_e32 v42, v33
	v_mul_f32_e32 v33, 0xbfb8aa3b, v39
	v_exp_f32_e32 v33, v33
	v_cvt_pk_bf16_f32 v36, v36, v37
	v_add_f32_e32 v2, v2, v3
	v_add_f32_e32 v0, v0, v2
	v_add_f32_e32 v33, 1.0, v33
	v_rcp_f32_e32 v43, v33
	s_nop 0
	v_pk_mul_f32 v[38:39], v[42:43], v[38:39]
	s_nop 0
	v_pk_mul_f32 v[38:39], v[38:39], v[40:41]
	s_nop 0
	v_cvt_pk_bf16_f32 v37, v38, v39
	global_store_dwordx2 v[18:19], v[36:37], off offset:64
	v_lshlrev_b32_e32 v36, 16, v118
	v_pk_mul_f32 v[38:39], v[4:5], v[32:33] op_sel_hi:[1,0]
	v_mul_f32_e32 v33, 0xbfb8aa3b, v36
	v_exp_f32_e32 v33, v33
	v_and_b32_e32 v37, 0xffff0000, v118
	v_pk_mul_f32 v[4:5], v[38:39], v[38:39]
	v_pk_mul_f32 v[38:39], v[72:73], v[38:39]
	v_add_f32_e32 v33, 1.0, v33
	v_rcp_f32_e32 v40, v33
	v_mul_f32_e32 v33, 0xbfb8aa3b, v37
	v_exp_f32_e32 v33, v33
	v_add_f32_e32 v2, v4, v5
	v_add_f32_e32 v33, 1.0, v33
	v_rcp_f32_e32 v41, v33
	s_nop 0
	v_pk_mul_f32 v[36:37], v[40:41], v[36:37]
	s_nop 0
	v_pk_mul_f32 v[36:37], v[36:37], v[38:39]
	v_lshlrev_b32_e32 v38, 16, v119
	v_pk_mul_f32 v[40:41], v[6:7], v[32:33] op_sel_hi:[1,0]
	v_mul_f32_e32 v33, 0xbfb8aa3b, v38
	v_exp_f32_e32 v33, v33
	v_and_b32_e32 v39, 0xffff0000, v119
	v_pk_mul_f32 v[6:7], v[40:41], v[40:41]
	v_pk_mul_f32 v[40:41], v[74:75], v[40:41]
	v_add_f32_e32 v33, 1.0, v33
	v_rcp_f32_e32 v42, v33
	v_mul_f32_e32 v33, 0xbfb8aa3b, v39
	v_exp_f32_e32 v33, v33
	v_cvt_pk_bf16_f32 v36, v36, v37
	v_add_f32_e32 v1, v6, v7
	v_add_f32_e32 v1, v2, v1
	v_add_f32_e32 v33, 1.0, v33
	v_rcp_f32_e32 v43, v33
	v_pk_mul_f32 v[8:9], v[8:9], v[32:33] op_sel_hi:[1,0]
	v_pk_mul_f32 v[38:39], v[42:43], v[38:39]
	s_nop 0
	v_pk_mul_f32 v[38:39], v[38:39], v[40:41]
	s_nop 0
	v_cvt_pk_bf16_f32 v37, v38, v39
	global_store_dwordx2 v[18:19], v[36:37], off offset:80
	v_lshlrev_b32_e32 v36, 16, v116
	v_mul_f32_e32 v33, 0xbfb8aa3b, v36
	v_exp_f32_e32 v33, v33
	v_and_b32_e32 v37, 0xffff0000, v116
	v_pk_mul_f32 v[38:39], v[8:9], v[8:9]
	v_pk_mul_f32 v[8:9], v[68:69], v[8:9]
	v_add_f32_e32 v33, 1.0, v33
	v_rcp_f32_e32 v40, v33
	v_mul_f32_e32 v33, 0xbfb8aa3b, v37
	v_exp_f32_e32 v33, v33
	v_add_f32_e32 v2, v38, v39
	v_add_f32_e32 v33, 1.0, v33
	v_rcp_f32_e32 v41, v33
	v_pk_mul_f32 v[10:11], v[10:11], v[32:33] op_sel_hi:[1,0]
	v_pk_mul_f32 v[36:37], v[40:41], v[36:37]
	s_nop 0
	v_pk_mul_f32 v[8:9], v[36:37], v[8:9]
	v_lshlrev_b32_e32 v36, 16, v117
	v_cvt_pk_bf16_f32 v8, v8, v9
	v_mul_f32_e32 v9, 0xbfb8aa3b, v36
	v_exp_f32_e32 v9, v9
	v_and_b32_e32 v37, 0xffff0000, v117
	v_pk_mul_f32 v[40:41], v[10:11], v[10:11]
	v_pk_mul_f32 v[10:11], v[70:71], v[10:11]
	v_add_f32_e32 v9, 1.0, v9
	v_rcp_f32_e32 v42, v9
	v_mul_f32_e32 v9, 0xbfb8aa3b, v37
	v_exp_f32_e32 v9, v9
	s_nop 0
	v_add_f32_e32 v9, 1.0, v9
	v_rcp_f32_e32 v43, v9
	s_nop 0
	v_pk_mul_f32 v[36:37], v[42:43], v[36:37]
	s_nop 0
	v_pk_mul_f32 v[10:11], v[36:37], v[10:11]
	s_nop 0
	v_cvt_pk_bf16_f32 v9, v10, v11
	global_store_dwordx2 v[18:19], v[8:9], off offset:96
	v_lshlrev_b32_e32 v8, 16, v114
	v_pk_mul_f32 v[10:11], v[12:13], v[32:33] op_sel_hi:[1,0]
	v_mul_f32_e32 v33, 0xbfb8aa3b, v8
	v_exp_f32_e32 v33, v33
	v_and_b32_e32 v9, 0xffff0000, v114
	v_pk_mul_f32 v[12:13], v[10:11], v[10:11]
	v_pk_mul_f32 v[10:11], v[64:65], v[10:11]
	v_add_f32_e32 v33, 1.0, v33
	v_rcp_f32_e32 v36, v33
	v_mul_f32_e32 v33, 0xbfb8aa3b, v9
	v_exp_f32_e32 v33, v33
	s_nop 0
	v_add_f32_e32 v33, 1.0, v33
	v_rcp_f32_e32 v37, v33
	v_pk_mul_f32 v[14:15], v[14:15], v[32:33] op_sel_hi:[1,0]
	v_pk_mul_f32 v[8:9], v[36:37], v[8:9]
	s_nop 0
	v_pk_mul_f32 v[8:9], v[8:9], v[10:11]
	v_pk_mul_f32 v[32:33], v[14:15], v[14:15]
	v_cvt_pk_bf16_f32 v8, v8, v9
	v_add_f32_e32 v9, v26, v27
	v_add_f32_e32 v9, v24, v9
	v_add_f32_e32 v9, v9, v16
	v_add_f32_e32 v16, v30, v31
	v_add_f32_e32 v16, v17, v16
	v_add_f32_e32 v9, v16, v9
	v_add_f32_e32 v0, v0, v9
	v_add_f32_e32 v0, v1, v0
	v_add_f32_e32 v1, v40, v41
	v_add_f32_e32 v1, v2, v1
	v_add_f32_e32 v0, v1, v0
	v_add_f32_e32 v1, v32, v33
	v_add_f32_e32 v2, v12, v13
	v_lshlrev_b32_e32 v10, 16, v115
	v_add_f32_e32 v1, v2, v1
	v_add_f32_e32 v0, v1, v0
	v_mul_f32_e32 v1, 0xbfb8aa3b, v10
	v_exp_f32_e32 v1, v1
	v_and_b32_e32 v11, 0xffff0000, v115
	v_pk_mul_f32 v[4:5], v[66:67], v[14:15]
	v_add_f32_e32 v1, 1.0, v1
	v_rcp_f32_e32 v2, v1
	v_mul_f32_e32 v1, 0xbfb8aa3b, v11
	v_exp_f32_e32 v1, v1
	s_nop 0
	v_add_f32_e32 v1, 1.0, v1
	v_rcp_f32_e32 v3, v1
	ds_bpermute_b32 v1, v133, v0
	v_pk_mul_f32 v[2:3], v[2:3], v[10:11]
	s_nop 0
	v_pk_mul_f32 v[2:3], v[2:3], v[4:5]
	s_nop 0
	v_cvt_pk_bf16_f32 v9, v2, v3
	global_store_dwordx2 v[18:19], v[8:9], off offset:112
	s_and_saveexec_b64 s[0:1], vcc
	s_cbranch_execz .LBB0_443
	s_add_u32 s4, s28, s4
	s_addc_u32 s5, s29, s5
	s_waitcnt lgkmcnt(0)
	v_add_f32_e32 v2, v0, v1
	v_lshlrev_b64 v[0:1], 5, v[112:113]
	v_lshl_add_u64 v[0:1], s[4:5], 0, v[0:1]
	v_lshlrev_b32_e32 v198, 2, v129
	v_lshl_add_u64 v[0:1], v[0:1], 0, v[198:199]
	global_store_dword v[0:1], v2, off
